# v20 + non-temporal hint on the final RMSNorm row loads and output stores
# speedup vs baseline: 1.0004x; 1.0004x over previous
; __global__ void __launch_bounds__(512, 2) fwd_kernel(Args args) {
;     ...
;         for (int m = gw; m < S; m += NGW) {
;             const float rs = rsqrtf(ssq_fin[m] * (1.0f / 1024.0f) + 1e-6f);
;             f32x4* xr = (f32x4*)(out + (size_t)m * D) + lane;
; #pragma unroll
;             for (int j = 0; j < 4; ++j) { const f32x4 gg = ((const f32x4*)gf + lane)[64 * j]; xr[64 * j] = xr[64 * j] * rs * gg; }
;         }
.LBB0_2571:
	global_load_dword v18, v1, s[0:1]
	global_load_dwordx4 v[6:9], v[4:5], off offset:-2048 nt
	global_load_dwordx4 v[10:13], v[2:3], off
	global_load_dwordx4 v[14:17], v[4:5], off offset:-1024 nt
	s_add_i32 s2, s2, s16
	s_add_u32 s0, s0, s4
	s_addc_u32 s1, s1, s5
	s_cmpk_gt_i32 s2, 0x3fff
	s_waitcnt vmcnt(3)
	v_fmamk_f32 v18, v18, 0x3a800000, v0
	v_mul_f32_e32 v19, 0x4b800000, v18
	v_cmp_gt_f32_e32 vcc, s3, v18
	s_nop 1
	v_cndmask_b32_e32 v18, v18, v19, vcc
	v_rsq_f32_e32 v18, v18
	s_nop 0
	v_mul_f32_e32 v19, 0x45800000, v18
	v_cndmask_b32_e32 v18, v18, v19, vcc
	s_waitcnt vmcnt(2)
	v_pk_mul_f32 v[6:7], v[18:19], v[6:7] op_sel_hi:[0,1]
	v_pk_mul_f32 v[8:9], v[18:19], v[8:9] op_sel_hi:[0,1]
	s_waitcnt vmcnt(1)
	v_pk_mul_f32 v[8:9], v[12:13], v[8:9]
	v_pk_mul_f32 v[6:7], v[10:11], v[6:7]
	global_store_dwordx4 v[4:5], v[6:9], off offset:-2048 nt
	global_load_dwordx4 v[6:9], v[2:3], off offset:1024
	s_nop 0
	global_load_dwordx4 v[10:13], v[4:5], off nt
	s_waitcnt vmcnt(3)
	v_pk_mul_f32 v[16:17], v[18:19], v[16:17] op_sel_hi:[0,1]
	v_pk_mul_f32 v[14:15], v[18:19], v[14:15] op_sel_hi:[0,1]
	s_waitcnt vmcnt(1)
	v_pk_mul_f32 v[6:7], v[6:7], v[14:15]
	v_pk_mul_f32 v[8:9], v[8:9], v[16:17]
	global_store_dwordx4 v[4:5], v[6:9], off offset:-1024 nt
	global_load_dwordx4 v[6:9], v[2:3], off offset:2048
	s_nop 0
	global_load_dwordx4 v[14:17], v[4:5], off offset:1024 nt
	s_waitcnt vmcnt(3)
	v_pk_mul_f32 v[12:13], v[18:19], v[12:13] op_sel_hi:[0,1]
	v_pk_mul_f32 v[10:11], v[18:19], v[10:11] op_sel_hi:[0,1]
	s_waitcnt vmcnt(1)
	v_pk_mul_f32 v[6:7], v[6:7], v[10:11]
	v_pk_mul_f32 v[8:9], v[8:9], v[12:13]
	global_store_dwordx4 v[4:5], v[6:9], off nt
	global_load_dwordx4 v[6:9], v[2:3], off offset:3072
	s_waitcnt vmcnt(2)
	v_pk_mul_f32 v[10:11], v[18:19], v[16:17] op_sel_hi:[0,1]
	v_pk_mul_f32 v[12:13], v[18:19], v[14:15] op_sel_hi:[0,1]
	s_waitcnt vmcnt(0)
	v_pk_mul_f32 v[6:7], v[6:7], v[12:13]
	v_pk_mul_f32 v[8:9], v[8:9], v[10:11]
	global_store_dwordx4 v[4:5], v[6:9], off offset:1024 nt
	v_lshl_add_u64 v[4:5], v[4:5], 0, s[6:7]
	s_cbranch_scc0 .LBB0_2571
